# P6 (squared-ReLU up GEMM) epilogue: the 8 row-sum-of-squares loads of a tile issued together at the top with a single wait (on top of v15b)
# baseline (speedup 1.0000x reference)
; __device__ __forceinline__ unsigned cvt_pk_bf16(float lo, float hi) { unsigned r; asm volatile("v_cvt_pk_bf16_f32 %0, %1, %2" : "=v"(r) : "v"(lo), "v"(hi)); return r; }
;     __device__ __forceinline__ void operator()(const f32x4 (&acc)[2][2][4][2], const Unit& u, int wr, int wc, int fr, int fq) const {
;         const int row0 = u.pm * BM + wr * 64 + fr;
;         const int col0 = u.pn * BM + wc * 32 + 8 * fq;
; #pragma unroll
;         for (int ai = 0; ai < 2; ++ai)
; #pragma unroll
;             for (int m = 0; m < 4; ++m) { bf16_t* rowp = O + (size_t)(row0 + ai * HALF + m * 16) * ldc + col0;
;                 const float r2 = 1.0f / (rowsq[row0 + ai * HALF + m * 16] * (1.0f / 2048.0f) + 1e-6f);
; #pragma unroll
;                 for (int bj = 0; bj < 2; ++bj) { f32x4 v0 = acc[ai][bj][m][0], v1 = acc[ai][bj][m][1];
; #pragma unroll
;                     for (int j = 0; j < 4; ++j) { const float a = fmaxf(v0[j], 0.f), b = fmaxf(v1[j], 0.f); v0[j] = a * a * r2; v1[j] = b * b * r2; }
;                     u32x4 w; w.x = cvt_pk_bf16(v0[0], v0[1]); w.y = cvt_pk_bf16(v0[2], v0[3]); w.z = cvt_pk_bf16(v1[0], v1[1]); w.w = cvt_pk_bf16(v1[2], v1[3]);
;                     __builtin_nontemporal_store(w, (u32x4*)(rowp + bj * HALF)); } }
.LBB0_2107:
	v_lshl_add_u32 v144, s30, 8, v1
	v_ashrrev_i32_e32 v145, 31, v144
	v_lshl_add_u64 v[142:143], v[144:145], 2, s[10:11]
	global_load_dword v244, v[142:143], off
	global_load_dword v245, v[142:143], off offset:64
	global_load_dword v246, v[142:143], off offset:128
	global_load_dword v247, v[142:143], off offset:192
	global_load_dword v248, v[142:143], off offset:512
	global_load_dword v249, v[142:143], off offset:576
	global_load_dword v250, v[142:143], off offset:640
	global_load_dword v251, v[142:143], off offset:704
	v_lshl_or_b32 v150, s27, 8, v147
	v_ashrrev_i32_e32 v151, 31, v150
	v_max_f32_e32 v153, 0, v116
	v_max_f32_e32 v155, 0, v118
	v_max_f32_e32 v152, 0, v124
	v_max_f32_e32 v154, 0, v117
	v_max_f32_e32 v156, 0, v119
	v_lshlrev_b64 v[118:119], 1, v[150:151]
	v_mul_f32_e32 v151, v153, v153
	v_mul_f32_e32 v153, v155, v155
	v_lshlrev_b64 v[116:117], 14, v[144:145]
	v_mul_f32_e32 v145, v152, v152
	v_mul_f32_e32 v152, v154, v154
	v_mul_f32_e32 v154, v156, v156
	v_max_f32_e32 v128, 0, v128
	v_max_f32_e32 v129, 0, v129
	v_max_f32_e32 v130, 0, v130
	v_max_f32_e32 v131, 0, v131
	v_max_f32_e32 v120, 0, v120
	v_max_f32_e32 v121, 0, v121
	v_max_f32_e32 v125, 0, v125
	v_max_f32_e32 v126, 0, v126
	v_max_f32_e32 v127, 0, v127
	v_max_f32_e32 v122, 0, v122
	v_max_f32_e32 v123, 0, v123
	v_mul_f32_e32 v128, v128, v128
	v_mul_f32_e32 v129, v129, v129
	v_mul_f32_e32 v130, v130, v130
	v_mul_f32_e32 v131, v131, v131
	v_mul_f32_e32 v120, v120, v120
	v_mul_f32_e32 v121, v121, v121
	v_lshl_add_u64 v[116:117], s[8:9], 0, v[116:117]
	v_or_b32_e32 v124, 16, v144
	v_mul_f32_e32 v150, v125, v125
	v_mul_f32_e32 v126, v126, v126
	v_mul_f32_e32 v127, v127, v127
	v_mul_f32_e32 v122, v122, v122
	v_mul_f32_e32 v123, v123, v123
	v_lshl_add_u64 v[116:117], v[116:117], 0, v[118:119]
	v_ashrrev_i32_e32 v125, 31, v124
	v_max_f32_e32 v100, 0, v100
	v_max_f32_e32 v101, 0, v101
	v_max_f32_e32 v108, 0, v108
	v_max_f32_e32 v109, 0, v109
	v_max_f32_e32 v112, 0, v112
	v_max_f32_e32 v113, 0, v113
	v_max_f32_e32 v114, 0, v114
	s_waitcnt vmcnt(0)
	v_fmamk_f32 v149, v244, 0x3a000000, v232
	v_div_scale_f32 v155, s[26:27], v149, v149, 1.0
	v_rcp_f32_e32 v156, v155
	v_div_scale_f32 v157, vcc, 1.0, v149, 1.0
	v_max_f32_e32 v110, 0, v110
	v_fma_f32 v158, -v155, v156, 1.0
	v_fmac_f32_e32 v156, v158, v156
	v_mul_f32_e32 v158, v157, v156
	v_fma_f32 v159, -v155, v158, v157
	v_fmac_f32_e32 v158, v159, v156
	v_fma_f32 v155, -v155, v158, v157
	v_div_fmas_f32 v155, v155, v156, v158
	v_div_fixup_f32 v149, v155, v149, 1.0
	v_mul_f32_e32 v128, v128, v149
	v_mul_f32_e32 v129, v129, v149
	v_mul_f32_e32 v130, v130, v149
	v_mul_f32_e32 v131, v131, v149
	v_mul_f32_e32 v155, v120, v149
	v_mul_f32_e32 v156, v121, v149
	v_cvt_pk_bf16_f32 v120, v128, v129
	v_cvt_pk_bf16_f32 v121, v130, v131
	v_mul_f32_e32 v145, v145, v149
	v_mul_f32_e32 v150, v150, v149
	v_mul_f32_e32 v126, v126, v149
	v_mul_f32_e32 v127, v127, v149
	v_mul_f32_e32 v157, v122, v149
	v_mul_f32_e32 v158, v123, v149
	v_cvt_pk_bf16_f32 v122, v145, v150
	v_cvt_pk_bf16_f32 v123, v126, v127
	global_store_dwordx4 v[116:117], v[120:123], off nt
	v_mul_f32_e32 v151, v151, v149
	v_mul_f32_e32 v152, v152, v149
	v_cvt_pk_bf16_f32 v120, v155, v156
	v_cvt_pk_bf16_f32 v121, v157, v158
	v_mul_f32_e32 v153, v153, v149
	v_mul_f32_e32 v149, v154, v149
	v_cvt_pk_bf16_f32 v122, v151, v152
	v_cvt_pk_bf16_f32 v123, v153, v149
	global_store_dwordx4 v[116:117], v[120:123], off offset:256 nt
	v_mul_f32_e32 v126, v100, v100
	v_mul_f32_e32 v128, v101, v101
	v_lshl_add_u64 v[120:121], v[124:125], 2, s[10:11]
	s_nop 0
	v_lshlrev_b64 v[100:101], 14, v[124:125]
	v_lshl_add_u64 v[100:101], s[8:9], 0, v[100:101]
	v_mul_f32_e32 v122, v108, v108
	v_mul_f32_e32 v123, v109, v109
	v_lshl_add_u64 v[108:109], v[100:101], 0, v[118:119]
	v_max_f32_e32 v115, 0, v115
	v_max_f32_e32 v111, 0, v111
	v_max_f32_e32 v121, 0, v104
	v_max_f32_e32 v105, 0, v105
	v_max_f32_e32 v106, 0, v106
	v_max_f32_e32 v102, 0, v102
	v_max_f32_e32 v107, 0, v107
	v_max_f32_e32 v103, 0, v103
	v_mul_f32_e32 v112, v112, v112
	v_or_b32_e32 v104, 32, v144
	v_mul_f32_e32 v113, v113, v113
	v_mul_f32_e32 v114, v114, v114
	v_mul_f32_e32 v110, v110, v110
	v_mul_f32_e32 v115, v115, v115
	v_mul_f32_e32 v111, v111, v111
	v_mul_f32_e32 v121, v121, v121
	v_mul_f32_e32 v127, v105, v105
	v_mul_f32_e32 v129, v106, v106
	v_mul_f32_e32 v102, v102, v102
	v_mul_f32_e32 v130, v107, v107
	v_mul_f32_e32 v103, v103, v103
	v_ashrrev_i32_e32 v105, 31, v104
	v_lshl_add_u64 v[106:107], v[104:105], 2, s[10:11]
	v_max_f32_e32 v84, 0, v84
	v_max_f32_e32 v85, 0, v85
	v_max_f32_e32 v92, 0, v92
	v_max_f32_e32 v93, 0, v93
	v_max_f32_e32 v96, 0, v96
	v_max_f32_e32 v97, 0, v97
	v_max_f32_e32 v98, 0, v98
	v_max_f32_e32 v94, 0, v94
	v_max_f32_e32 v99, 0, v99
	v_max_f32_e32 v95, 0, v95
	v_max_f32_e32 v89, 0, v89
	v_max_f32_e32 v90, 0, v90
	v_max_f32_e32 v86, 0, v86
	v_max_f32_e32 v91, 0, v91
	v_max_f32_e32 v87, 0, v87
	v_mul_f32_e32 v96, v96, v96
	v_mul_f32_e32 v97, v97, v97
	v_mul_f32_e32 v98, v98, v98
	v_mul_f32_e32 v94, v94, v94
	v_mul_f32_e32 v99, v99, v99
	v_mul_f32_e32 v95, v95, v95
	v_mul_f32_e32 v86, v86, v86
	v_mul_f32_e32 v87, v87, v87
	v_max_f32_e32 v68, 0, v68
	v_max_f32_e32 v69, 0, v69
	v_max_f32_e32 v72, 0, v72
	v_max_f32_e32 v73, 0, v73
	s_nop 0
	v_fmamk_f32 v120, v245, 0x3a000000, v232
	v_div_scale_f32 v124, s[26:27], v120, v120, 1.0
	v_rcp_f32_e32 v125, v124
	v_div_scale_f32 v100, vcc, 1.0, v120, 1.0
	v_fma_f32 v101, -v124, v125, 1.0
	v_fmac_f32_e32 v125, v101, v125
	v_mul_f32_e32 v101, v100, v125
	v_fma_f32 v131, -v124, v101, v100
	v_fmac_f32_e32 v101, v131, v125
	v_fma_f32 v100, -v124, v101, v100
	v_div_fmas_f32 v100, v100, v125, v101
; __device__ __forceinline__ unsigned cvt_pk_bf16(float lo, float hi) { unsigned r; asm volatile("v_cvt_pk_bf16_f32 %0, %1, %2" : "=v"(r) : "v"(lo), "v"(hi)); return r; }
;     __device__ __forceinline__ void operator()(const f32x4 (&acc)[2][2][4][2], const Unit& u, int wr, int wc, int fr, int fq) const {
;         const int row0 = u.pm * BM + wr * 64 + fr;
;         const int col0 = u.pn * BM + wc * 32 + 8 * fq;
; #pragma unroll
;         for (int ai = 0; ai < 2; ++ai)
; #pragma unroll
;             for (int m = 0; m < 4; ++m) { bf16_t* rowp = O + (size_t)(row0 + ai * HALF + m * 16) * ldc + col0;
;                 const float r2 = 1.0f / (rowsq[row0 + ai * HALF + m * 16] * (1.0f / 2048.0f) + 1e-6f);
; #pragma unroll
;                 for (int bj = 0; bj < 2; ++bj) { f32x4 v0 = acc[ai][bj][m][0], v1 = acc[ai][bj][m][1];
; #pragma unroll
;                     for (int j = 0; j < 4; ++j) { const float a = fmaxf(v0[j], 0.f), b = fmaxf(v1[j], 0.f); v0[j] = a * a * r2; v1[j] = b * b * r2; }
;                     u32x4 w; w.x = cvt_pk_bf16(v0[0], v0[1]); w.y = cvt_pk_bf16(v0[2], v0[3]); w.z = cvt_pk_bf16(v1[0], v1[1]); w.w = cvt_pk_bf16(v1[2], v1[3]);
;                     __builtin_nontemporal_store(w, (u32x4*)(rowp + bj * HALF)); } }
	v_div_fixup_f32 v100, v100, v120, 1.0
	v_mul_f32_e32 v101, v112, v100
	v_mul_f32_e32 v112, v122, v100
	v_mul_f32_e32 v113, v113, v100
	v_mul_f32_e32 v120, v123, v100
	v_mul_f32_e32 v114, v114, v100
	v_mul_f32_e32 v110, v110, v100
	v_mul_f32_e32 v115, v115, v100
	v_mul_f32_e32 v111, v111, v100
	v_mul_f32_e32 v121, v121, v100
	v_mul_f32_e32 v122, v126, v100
	v_mul_f32_e32 v123, v127, v100
	v_mul_f32_e32 v124, v128, v100
	v_mul_f32_e32 v125, v129, v100
	v_mul_f32_e32 v126, v102, v100
	v_mul_f32_e32 v127, v130, v100
	v_mul_f32_e32 v128, v103, v100
	v_cvt_pk_bf16_f32 v100, v101, v113
	v_cvt_pk_bf16_f32 v101, v114, v115
	v_cvt_pk_bf16_f32 v102, v112, v120
	v_cvt_pk_bf16_f32 v103, v110, v111
	global_store_dwordx4 v[108:109], v[100:103], off nt
	v_mul_f32_e32 v110, v91, v91
	s_nop 0
	v_cvt_pk_bf16_f32 v100, v121, v123
	v_cvt_pk_bf16_f32 v101, v125, v127
	v_cvt_pk_bf16_f32 v102, v122, v124
	v_cvt_pk_bf16_f32 v103, v126, v128
	global_store_dwordx4 v[108:109], v[100:103], off offset:256 nt
	s_nop 0
	v_mul_f32_e32 v106, v84, v84
	v_mul_f32_e32 v108, v85, v85
	v_lshlrev_b64 v[84:85], 14, v[104:105]
	v_lshl_add_u64 v[84:85], s[8:9], 0, v[84:85]
	v_mul_f32_e32 v102, v92, v92
	v_mul_f32_e32 v103, v93, v93
	v_lshl_add_u64 v[92:93], v[84:85], 0, v[118:119]
	v_max_f32_e32 v101, 0, v88
	v_or_b32_e32 v88, 48, v144
	v_mul_f32_e32 v101, v101, v101
	v_mul_f32_e32 v107, v89, v89
	v_mul_f32_e32 v109, v90, v90
	v_ashrrev_i32_e32 v89, 31, v88
	v_lshl_add_u64 v[90:91], v[88:89], 2, s[10:11]
	v_max_f32_e32 v80, 0, v80
	v_max_f32_e32 v76, 0, v76
	v_max_f32_e32 v81, 0, v81
	v_max_f32_e32 v77, 0, v77
	v_max_f32_e32 v82, 0, v82
	v_max_f32_e32 v78, 0, v78
	v_max_f32_e32 v83, 0, v83
	v_max_f32_e32 v79, 0, v79
	v_max_f32_e32 v74, 0, v74
	v_max_f32_e32 v70, 0, v70
	v_max_f32_e32 v75, 0, v75
	v_max_f32_e32 v71, 0, v71
	v_mul_f32_e32 v80, v80, v80
	v_mul_f32_e32 v76, v76, v76
	v_mul_f32_e32 v81, v81, v81
	v_mul_f32_e32 v77, v77, v77
	v_mul_f32_e32 v82, v82, v82
	v_mul_f32_e32 v78, v78, v78
	v_mul_f32_e32 v83, v83, v83
	v_mul_f32_e32 v79, v79, v79
	v_mul_f32_e32 v74, v74, v74
	v_mul_f32_e32 v70, v70, v70
	v_mul_f32_e32 v75, v75, v75
	v_mul_f32_e32 v71, v71, v71
	v_max_f32_e32 v56, 0, v56
	v_max_f32_e32 v57, 0, v57
	v_max_f32_e32 v58, 0, v58
	s_mov_b32 s15, 0x200000
	v_max_f32_e32 v59, 0, v59
	v_max_f32_e32 v64, 0, v64
	v_max_f32_e32 v60, 0, v60
	v_max_f32_e32 v65, 0, v65
	v_max_f32_e32 v61, 0, v61
	v_max_f32_e32 v66, 0, v66
	v_max_f32_e32 v62, 0, v62
	v_max_f32_e32 v67, 0, v67
	v_max_f32_e32 v63, 0, v63
	v_max_f32_e32 v52, 0, v52
	v_max_f32_e32 v53, 0, v53
	v_max_f32_e32 v54, 0, v54
	v_max_f32_e32 v55, 0, v55
	v_mul_f32_e32 v64, v64, v64
	v_mul_f32_e32 v60, v60, v60
	s_nop 0
	v_fmamk_f32 v100, v246, 0x3a000000, v232
	v_div_scale_f32 v104, s[26:27], v100, v100, 1.0
	v_rcp_f32_e32 v105, v104
	v_div_scale_f32 v84, vcc, 1.0, v100, 1.0
	v_mul_f32_e32 v65, v65, v65
	v_fma_f32 v85, -v104, v105, 1.0
	v_fmac_f32_e32 v105, v85, v105
	v_mul_f32_e32 v85, v84, v105
	v_fma_f32 v111, -v104, v85, v84
	v_fmac_f32_e32 v85, v111, v105
	v_fma_f32 v84, -v104, v85, v84
	v_div_fmas_f32 v84, v84, v105, v85
	v_div_fixup_f32 v84, v84, v100, 1.0
	v_mul_f32_e32 v85, v96, v84
	v_mul_f32_e32 v96, v102, v84
	v_mul_f32_e32 v97, v97, v84
	v_mul_f32_e32 v100, v103, v84
	v_mul_f32_e32 v98, v98, v84
	v_mul_f32_e32 v94, v94, v84
	v_mul_f32_e32 v99, v99, v84
	v_mul_f32_e32 v95, v95, v84
	v_mul_f32_e32 v101, v101, v84
	v_mul_f32_e32 v102, v106, v84
	v_mul_f32_e32 v103, v107, v84
	v_mul_f32_e32 v104, v108, v84
	v_mul_f32_e32 v105, v109, v84
	v_mul_f32_e32 v106, v86, v84
	v_mul_f32_e32 v107, v110, v84
	v_mul_f32_e32 v108, v87, v84
	v_cvt_pk_bf16_f32 v84, v85, v97
	v_cvt_pk_bf16_f32 v85, v98, v99
	v_cvt_pk_bf16_f32 v86, v96, v100
	v_cvt_pk_bf16_f32 v87, v94, v95
	global_store_dwordx4 v[92:93], v[84:87], off nt
	v_mul_f32_e32 v61, v61, v61
	v_mul_f32_e32 v66, v66, v66
	v_cvt_pk_bf16_f32 v84, v101, v103
	v_cvt_pk_bf16_f32 v85, v105, v107
	v_cvt_pk_bf16_f32 v86, v102, v104
	v_cvt_pk_bf16_f32 v87, v106, v108
	global_store_dwordx4 v[92:93], v[84:87], off offset:256 nt
	s_nop 0
	v_mul_f32_e32 v90, v69, v69
	v_mul_f32_e32 v86, v68, v68
	v_lshlrev_b64 v[68:69], 14, v[88:89]
	v_lshl_add_u64 v[68:69], s[8:9], 0, v[68:69]
	v_mul_f32_e32 v85, v72, v72
	v_mul_f32_e32 v87, v73, v73
	v_lshl_add_u64 v[72:73], v[68:69], 0, v[118:119]
	v_mul_f32_e32 v62, v62, v62
	v_mul_f32_e32 v67, v67, v67
	v_mul_f32_e32 v63, v63, v63
	v_mul_f32_e32 v52, v52, v52
	v_mul_f32_e32 v53, v53, v53
	v_mul_f32_e32 v54, v54, v54
	v_mul_f32_e32 v55, v55, v55
	v_max_f32_e32 v40, 0, v40
	v_max_f32_e32 v41, 0, v41
	v_max_f32_e32 v42, 0, v42
	v_max_f32_e32 v43, 0, v43
	v_max_f32_e32 v48, 0, v48
	v_max_f32_e32 v44, 0, v44
	v_max_f32_e32 v49, 0, v49
	v_max_f32_e32 v45, 0, v45
	v_max_f32_e32 v50, 0, v50
	v_max_f32_e32 v46, 0, v46
	v_max_f32_e32 v51, 0, v51
	v_max_f32_e32 v47, 0, v47
	v_max_f32_e32 v36, 0, v36
	v_max_f32_e32 v37, 0, v37
	v_max_f32_e32 v38, 0, v38
	v_max_f32_e32 v39, 0, v39
	v_mul_f32_e32 v48, v48, v48
	v_mul_f32_e32 v44, v44, v44
	v_mul_f32_e32 v49, v49, v49
	v_mul_f32_e32 v45, v45, v45
	v_mul_f32_e32 v50, v50, v50
	v_mul_f32_e32 v46, v46, v46
	v_mul_f32_e32 v51, v51, v51
	v_mul_f32_e32 v47, v47, v47
	v_mul_f32_e32 v36, v36, v36
	v_mul_f32_e32 v37, v37, v37
	v_mul_f32_e32 v38, v38, v38
	v_mul_f32_e32 v39, v39, v39
	v_max_f32_e32 v24, 0, v24
	v_max_f32_e32 v25, 0, v25
	v_max_f32_e32 v26, 0, v26
	v_max_f32_e32 v27, 0, v27
	v_max_f32_e32 v32, 0, v32
	s_nop 0
	v_fmamk_f32 v84, v247, 0x3a000000, v232
	v_div_scale_f32 v88, s[26:27], v84, v84, 1.0
	v_rcp_f32_e32 v89, v88
	v_div_scale_f32 v68, vcc, 1.0, v84, 1.0
	s_mov_b64 s[26:27], 0x200000
; __device__ __forceinline__ unsigned cvt_pk_bf16(float lo, float hi) { unsigned r; asm volatile("v_cvt_pk_bf16_f32 %0, %1, %2" : "=v"(r) : "v"(lo), "v"(hi)); return r; }
;     __device__ __forceinline__ void operator()(const f32x4 (&acc)[2][2][4][2], const Unit& u, int wr, int wc, int fr, int fq) const {
;     ...
;             for (int m = 0; m < 4; ++m) { bf16_t* rowp = O + (size_t)(row0 + ai * HALF + m * 16) * ldc + col0;
;                 const float r2 = 1.0f / (rowsq[row0 + ai * HALF + m * 16] * (1.0f / 2048.0f) + 1e-6f);
; #pragma unroll
;                 for (int bj = 0; bj < 2; ++bj) { f32x4 v0 = acc[ai][bj][m][0], v1 = acc[ai][bj][m][1];
; #pragma unroll
;                     for (int j = 0; j < 4; ++j) { const float a = fmaxf(v0[j], 0.f), b = fmaxf(v1[j], 0.f); v0[j] = a * a * r2; v1[j] = b * b * r2; }
;                     u32x4 w; w.x = cvt_pk_bf16(v0[0], v0[1]); w.y = cvt_pk_bf16(v0[2], v0[3]); w.z = cvt_pk_bf16(v1[0], v1[1]); w.w = cvt_pk_bf16(v1[2], v1[3]);
;                     __builtin_nontemporal_store(w, (u32x4*)(rowp + bj * HALF)); } }
	v_fma_f32 v69, -v88, v89, 1.0
	v_fmac_f32_e32 v89, v69, v89
	v_mul_f32_e32 v69, v68, v89
	v_fma_f32 v91, -v88, v69, v68
	v_fmac_f32_e32 v69, v91, v89
	v_fma_f32 v68, -v88, v69, v68
	v_div_fmas_f32 v68, v68, v89, v69
	v_div_fixup_f32 v68, v68, v84, 1.0
	v_mul_f32_e32 v69, v80, v68
	v_mul_f32_e32 v76, v76, v68
	v_mul_f32_e32 v80, v81, v68
	v_mul_f32_e32 v77, v77, v68
	v_mul_f32_e32 v81, v82, v68
	v_mul_f32_e32 v78, v78, v68
	v_mul_f32_e32 v82, v83, v68
	v_mul_f32_e32 v79, v79, v68
	v_mul_f32_e32 v83, v85, v68
	v_mul_f32_e32 v84, v86, v68
	v_mul_f32_e32 v85, v87, v68
	v_mul_f32_e32 v86, v90, v68
	v_mul_f32_e32 v74, v74, v68
	v_mul_f32_e32 v87, v70, v68
	v_mul_f32_e32 v75, v75, v68
	v_mul_f32_e32 v88, v71, v68
	v_cvt_pk_bf16_f32 v68, v69, v80
	v_cvt_pk_bf16_f32 v69, v81, v82
	v_cvt_pk_bf16_f32 v70, v76, v77
	v_cvt_pk_bf16_f32 v71, v78, v79
	global_store_dwordx4 v[72:73], v[68:71], off nt
	v_max_f32_e32 v28, 0, v28
	v_max_f32_e32 v33, 0, v33
	v_cvt_pk_bf16_f32 v68, v83, v85
	v_cvt_pk_bf16_f32 v69, v74, v75
	v_cvt_pk_bf16_f32 v70, v84, v86
	v_cvt_pk_bf16_f32 v71, v87, v88
	global_store_dwordx4 v[72:73], v[68:71], off offset:256 nt
	s_nop 0
	v_mul_f32_e32 v72, v59, v59
	v_mul_f32_e32 v69, v56, v56
	v_mul_f32_e32 v70, v57, v57
	v_lshl_add_u64 v[56:57], v[116:117], 0, s[26:27]
	v_mul_f32_e32 v71, v58, v58
	v_add_co_u32_e32 v58, vcc, s15, v116
	s_mov_b32 s15, 0x240000
	s_nop 0
	v_addc_co_u32_e32 v59, vcc, 0, v117, vcc
	v_max_f32_e32 v29, 0, v29
	v_max_f32_e32 v34, 0, v34
	v_max_f32_e32 v30, 0, v30
	v_max_f32_e32 v35, 0, v35
	v_max_f32_e32 v31, 0, v31
	v_max_f32_e32 v20, 0, v20
	v_max_f32_e32 v21, 0, v21
	v_max_f32_e32 v22, 0, v22
	v_max_f32_e32 v23, 0, v23
	v_mul_f32_e32 v32, v32, v32
	v_mul_f32_e32 v28, v28, v28
	v_mul_f32_e32 v33, v33, v33
	v_mul_f32_e32 v29, v29, v29
	v_mul_f32_e32 v34, v34, v34
	v_mul_f32_e32 v30, v30, v30
	v_mul_f32_e32 v35, v35, v35
	v_mul_f32_e32 v31, v31, v31
	v_mul_f32_e32 v20, v20, v20
	v_mul_f32_e32 v21, v21, v21
	v_mul_f32_e32 v22, v22, v22
	v_mul_f32_e32 v23, v23, v23
	v_max_f32_e32 v8, 0, v8
	v_max_f32_e32 v9, 0, v9
	v_max_f32_e32 v10, 0, v10
	v_max_f32_e32 v11, 0, v11
	v_max_f32_e32 v16, 0, v16
	v_max_f32_e32 v12, 0, v12
	v_max_f32_e32 v17, 0, v17
	v_max_f32_e32 v13, 0, v13
	v_max_f32_e32 v18, 0, v18
	v_max_f32_e32 v14, 0, v14
	v_max_f32_e32 v19, 0, v19
	v_max_f32_e32 v15, 0, v15
	v_max_f32_e32 v4, 0, v4
	v_max_f32_e32 v5, 0, v5
	v_max_f32_e32 v6, 0, v6
	v_max_f32_e32 v7, 0, v7
	v_mul_f32_e32 v16, v16, v16
	v_mul_f32_e32 v12, v12, v12
	v_mul_f32_e32 v17, v17, v17
	v_mul_f32_e32 v13, v13, v13
	v_mul_f32_e32 v18, v18, v18
	v_mul_f32_e32 v14, v14, v14
	v_mul_f32_e32 v19, v19, v19
	v_mul_f32_e32 v15, v15, v15
	v_mul_f32_e32 v4, v4, v4
	v_mul_f32_e32 v5, v5, v5
	v_mul_f32_e32 v6, v6, v6
	v_mul_f32_e32 v7, v7, v7
	s_nop 0
	v_fmamk_f32 v68, v248, 0x3a000000, v232
	v_div_scale_f32 v73, s[26:27], v68, v68, 1.0
	v_rcp_f32_e32 v74, v73
	v_div_scale_f32 v75, vcc, 1.0, v68, 1.0
	s_mov_b64 s[26:27], 0x240000
	v_fma_f32 v76, -v73, v74, 1.0
	v_fmac_f32_e32 v74, v76, v74
	v_mul_f32_e32 v76, v75, v74
	v_fma_f32 v77, -v73, v76, v75
	v_fmac_f32_e32 v76, v77, v74
	v_fma_f32 v73, -v73, v76, v75
	v_div_fmas_f32 v73, v73, v74, v76
	v_div_fixup_f32 v68, v73, v68, 1.0
	v_mul_f32_e32 v64, v64, v68
	v_mul_f32_e32 v60, v60, v68
	v_mul_f32_e32 v65, v65, v68
	v_mul_f32_e32 v61, v61, v68
	v_mul_f32_e32 v66, v66, v68
	v_mul_f32_e32 v62, v62, v68
	v_mul_f32_e32 v67, v67, v68
	v_mul_f32_e32 v63, v63, v68
	v_mul_f32_e32 v69, v69, v68
	v_mul_f32_e32 v73, v52, v68
	v_mul_f32_e32 v70, v70, v68
	v_mul_f32_e32 v74, v53, v68
	v_mul_f32_e32 v71, v71, v68
	v_mul_f32_e32 v75, v54, v68
	v_mul_f32_e32 v72, v72, v68
	v_mul_f32_e32 v68, v55, v68
	v_cvt_pk_bf16_f32 v52, v64, v65
	v_cvt_pk_bf16_f32 v53, v66, v67
	v_cvt_pk_bf16_f32 v54, v60, v61
	v_cvt_pk_bf16_f32 v55, v62, v63
	global_store_dwordx4 v[58:59], v[52:55], off nt
	s_nop 1
	v_cvt_pk_bf16_f32 v52, v69, v70
	v_cvt_pk_bf16_f32 v53, v71, v72
	v_cvt_pk_bf16_f32 v54, v73, v74
	v_cvt_pk_bf16_f32 v55, v75, v68
	global_store_dwordx4 v[56:57], v[52:55], off offset:256 nt
	s_nop 0
	v_mul_f32_e32 v56, v43, v43
	v_mul_f32_e32 v53, v40, v40
	v_mul_f32_e32 v54, v41, v41
	v_lshl_add_u64 v[40:41], v[116:117], 0, s[26:27]
	v_mul_f32_e32 v55, v42, v42
	v_add_co_u32_e32 v42, vcc, s15, v116
	s_mov_b32 s15, 0x280000
	s_nop 0
	v_addc_co_u32_e32 v43, vcc, 0, v117, vcc
	s_nop 0
	v_fmamk_f32 v52, v249, 0x3a000000, v232
	v_div_scale_f32 v57, s[26:27], v52, v52, 1.0
; __device__ __forceinline__ unsigned cvt_pk_bf16(float lo, float hi) { unsigned r; asm volatile("v_cvt_pk_bf16_f32 %0, %1, %2" : "=v"(r) : "v"(lo), "v"(hi)); return r; }
; #define PG8_BAR __builtin_amdgcn_s_barrier()
;     __device__ __forceinline__ void operator()(const f32x4 (&acc)[2][2][4][2], const Unit& u, int wr, int wc, int fr, int fq) const {
;     ...
;             for (int m = 0; m < 4; ++m) { bf16_t* rowp = O + (size_t)(row0 + ai * HALF + m * 16) * ldc + col0;
;                 const float r2 = 1.0f / (rowsq[row0 + ai * HALF + m * 16] * (1.0f / 2048.0f) + 1e-6f);
; #pragma unroll
;                 for (int bj = 0; bj < 2; ++bj) { f32x4 v0 = acc[ai][bj][m][0], v1 = acc[ai][bj][m][1];
; #pragma unroll
;                     for (int j = 0; j < 4; ++j) { const float a = fmaxf(v0[j], 0.f), b = fmaxf(v1[j], 0.f); v0[j] = a * a * r2; v1[j] = b * b * r2; }
;                     u32x4 w; w.x = cvt_pk_bf16(v0[0], v0[1]); w.y = cvt_pk_bf16(v0[2], v0[3]); w.z = cvt_pk_bf16(v1[0], v1[1]); w.w = cvt_pk_bf16(v1[2], v1[3]);
;                     __builtin_nontemporal_store(w, (u32x4*)(rowp + bj * HALF)); } }
; template <class Epi, class Sched, bool ALIGN_EPI = false, bool SP2 = false>
; __device__ __forceinline__ void gemm_phase(PG8_LAS unsigned char* lds, const Gemm g, const Sched& S, const Epi& E) {
;     ...
;         if constexpr (!Epi::AFTER_DRAIN) { E(acc, cur, wr, wc, fr, fq); S.done(cur); }
;         if (!has_next) break;
; #pragma unroll
;         for (int a = 0; a < 2; ++a)
; #pragma unroll
;             for (int b = 0; b < 2; ++b)
; #pragma unroll
;                 for (int m = 0; m < 4; ++m)
; #pragma unroll
;                     for (int n = 0; n < 2; ++n) acc[a][b][m][n] = (f32x4){0.f, 0.f, 0.f, 0.f};
;         cur = nxt; cA = nA; cB = nB; ++ui;
;         if constexpr (ALIGN_EPI) { if (wr == 1) PG8_BAR; }
	v_rcp_f32_e32 v58, v57
	v_div_scale_f32 v59, vcc, 1.0, v52, 1.0
	s_mov_b64 s[26:27], 0x280000
	v_fma_f32 v60, -v57, v58, 1.0
	v_fmac_f32_e32 v58, v60, v58
	v_mul_f32_e32 v60, v59, v58
	v_fma_f32 v61, -v57, v60, v59
	v_fmac_f32_e32 v60, v61, v58
	v_fma_f32 v57, -v57, v60, v59
	v_div_fmas_f32 v57, v57, v58, v60
	v_div_fixup_f32 v52, v57, v52, 1.0
	v_mul_f32_e32 v48, v48, v52
	v_mul_f32_e32 v44, v44, v52
	v_mul_f32_e32 v49, v49, v52
	v_mul_f32_e32 v45, v45, v52
	v_mul_f32_e32 v50, v50, v52
	v_mul_f32_e32 v46, v46, v52
	v_mul_f32_e32 v51, v51, v52
	v_mul_f32_e32 v47, v47, v52
	v_mul_f32_e32 v53, v53, v52
	v_mul_f32_e32 v57, v36, v52
	v_mul_f32_e32 v54, v54, v52
	v_mul_f32_e32 v58, v37, v52
	v_mul_f32_e32 v55, v55, v52
	v_mul_f32_e32 v59, v38, v52
	v_mul_f32_e32 v56, v56, v52
	v_mul_f32_e32 v52, v39, v52
	v_cvt_pk_bf16_f32 v36, v48, v49
	v_cvt_pk_bf16_f32 v37, v50, v51
	v_cvt_pk_bf16_f32 v38, v44, v45
	v_cvt_pk_bf16_f32 v39, v46, v47
	global_store_dwordx4 v[42:43], v[36:39], off nt
	s_nop 1
	v_cvt_pk_bf16_f32 v36, v53, v54
	v_cvt_pk_bf16_f32 v37, v55, v56
	v_cvt_pk_bf16_f32 v38, v57, v58
	v_cvt_pk_bf16_f32 v39, v59, v52
	global_store_dwordx4 v[40:41], v[36:39], off offset:256 nt
	s_nop 0
	v_mul_f32_e32 v40, v27, v27
	v_mul_f32_e32 v37, v24, v24
	v_mul_f32_e32 v38, v25, v25
	v_lshl_add_u64 v[24:25], v[116:117], 0, s[26:27]
	v_mul_f32_e32 v39, v26, v26
	v_add_co_u32_e32 v26, vcc, s15, v116
	s_mov_b32 s15, 0x2c0000
	s_nop 0
	v_addc_co_u32_e32 v27, vcc, 0, v117, vcc
	s_nop 0
	v_fmamk_f32 v36, v250, 0x3a000000, v232
	v_div_scale_f32 v41, s[26:27], v36, v36, 1.0
	v_rcp_f32_e32 v42, v41
	v_div_scale_f32 v43, vcc, 1.0, v36, 1.0
	s_mov_b64 s[26:27], 0x2c0000
	v_fma_f32 v44, -v41, v42, 1.0
	v_fmac_f32_e32 v42, v44, v42
	v_mul_f32_e32 v44, v43, v42
	v_fma_f32 v45, -v41, v44, v43
	v_fmac_f32_e32 v44, v45, v42
	v_fma_f32 v41, -v41, v44, v43
	v_div_fmas_f32 v41, v41, v42, v44
	v_div_fixup_f32 v36, v41, v36, 1.0
	v_mul_f32_e32 v32, v32, v36
	v_mul_f32_e32 v28, v28, v36
	v_mul_f32_e32 v33, v33, v36
	v_mul_f32_e32 v29, v29, v36
	v_mul_f32_e32 v34, v34, v36
	v_mul_f32_e32 v30, v30, v36
	v_mul_f32_e32 v35, v35, v36
	v_mul_f32_e32 v31, v31, v36
	v_mul_f32_e32 v37, v37, v36
	v_mul_f32_e32 v41, v20, v36
	v_mul_f32_e32 v38, v38, v36
	v_mul_f32_e32 v42, v21, v36
	v_mul_f32_e32 v39, v39, v36
	v_mul_f32_e32 v43, v22, v36
	v_mul_f32_e32 v40, v40, v36
	v_mul_f32_e32 v36, v23, v36
	v_cvt_pk_bf16_f32 v20, v32, v33
	v_cvt_pk_bf16_f32 v21, v34, v35
	v_cvt_pk_bf16_f32 v22, v28, v29
	v_cvt_pk_bf16_f32 v23, v30, v31
	global_store_dwordx4 v[26:27], v[20:23], off nt
	s_nop 1
	v_cvt_pk_bf16_f32 v20, v37, v38
	v_cvt_pk_bf16_f32 v21, v39, v40
	v_cvt_pk_bf16_f32 v22, v41, v42
	v_cvt_pk_bf16_f32 v23, v43, v36
	global_store_dwordx4 v[24:25], v[20:23], off offset:256 nt
	s_nop 0
	v_mul_f32_e32 v24, v11, v11
	v_mul_f32_e32 v21, v8, v8
	v_mul_f32_e32 v22, v9, v9
	v_lshl_add_u64 v[8:9], v[116:117], 0, s[26:27]
	v_mul_f32_e32 v23, v10, v10
	v_add_co_u32_e32 v10, vcc, s15, v116
	s_nop 0
	v_fmamk_f32 v20, v251, 0x3a000000, v232
	v_div_scale_f32 v25, s[26:27], v20, v20, 1.0
	v_rcp_f32_e32 v26, v25
	v_addc_co_u32_e32 v11, vcc, 0, v117, vcc
	v_div_scale_f32 v27, vcc, 1.0, v20, 1.0
	v_fma_f32 v28, -v25, v26, 1.0
	v_fmac_f32_e32 v26, v28, v26
	v_mul_f32_e32 v28, v27, v26
	v_fma_f32 v29, -v25, v28, v27
	v_fmac_f32_e32 v28, v29, v26
	v_fma_f32 v25, -v25, v28, v27
	v_div_fmas_f32 v25, v25, v26, v28
	v_div_fixup_f32 v20, v25, v20, 1.0
	s_andn2_b64 vcc, exec, s[4:5]
	v_mul_f32_e32 v16, v16, v20
	v_mul_f32_e32 v12, v12, v20
	v_mul_f32_e32 v17, v17, v20
	v_mul_f32_e32 v13, v13, v20
	v_mul_f32_e32 v18, v18, v20
	v_mul_f32_e32 v14, v14, v20
	v_mul_f32_e32 v19, v19, v20
	v_mul_f32_e32 v15, v15, v20
	v_mul_f32_e32 v21, v21, v20
	v_mul_f32_e32 v25, v4, v20
	v_mul_f32_e32 v22, v22, v20
	v_mul_f32_e32 v26, v5, v20
	v_mul_f32_e32 v23, v23, v20
	v_mul_f32_e32 v27, v6, v20
	v_mul_f32_e32 v24, v24, v20
	v_mul_f32_e32 v20, v7, v20
	v_cvt_pk_bf16_f32 v4, v16, v17
	v_cvt_pk_bf16_f32 v5, v18, v19
	v_cvt_pk_bf16_f32 v6, v12, v13
	v_cvt_pk_bf16_f32 v7, v14, v15
	s_mov_b64 s[4:5], -1
	global_store_dwordx4 v[10:11], v[4:7], off nt
	s_nop 1
	v_cvt_pk_bf16_f32 v4, v21, v22
	v_cvt_pk_bf16_f32 v5, v23, v24
	v_cvt_pk_bf16_f32 v6, v25, v26
	v_cvt_pk_bf16_f32 v7, v27, v20
	global_store_dwordx4 v[8:9], v[4:7], off offset:256 nt
	s_cbranch_vccnz .LBB0_2096
	s_andn2_b64 vcc, exec, s[6:7]
	s_cbranch_vccnz .LBB0_2095
	s_barrier
	s_branch .LBB0_2095
